# pipelined attention v4 plus s_setprio 1 during the MFMA block
# speedup vs baseline: 1.0371x; 1.0150x over previous
; #define MFMA32(a, b, c) __builtin_amdgcn_mfma_f32_32x32x16_bf16((a), (b), (c), 0, 0, 0)
; DI unsigned pk2(float a, float b) { f32x2 v = {a, b}; return __builtin_bit_cast(unsigned, __builtin_convertvector(v, bfv2)); }
; DI void attn_s(const unsigned char* sK, int tt, int qb, int qs, int sub, int l31, int h,
;                const bf16x8 (&qf)[4], f32x16 (&O)[4], float& m, float& l, bf16x8 (&pb)[4]) {
;     ...
;     for (int k2 = 0; k2 < 2; ++k2)
; #pragma unroll
;         for (int i = 0; i < 16; ++i) st[k2][i] = -m;
;     {
;         const unsigned char* kb = sK + l31 * A_KROWB + (sub * 64 + 8 * h) * 2;
;         bf16x8 ka[4], kc[4];
; #pragma unroll
;         for (int i = 0; i < 4; ++i) ka[i] = *(const bf16x8*)(kb + (i & 1) * 32 * A_KROWB + (i >> 1) * 32);
;         __builtin_amdgcn_sched_barrier(0);
; #pragma unroll
;         for (int i = 0; i < 4; ++i) kc[i] = *(const bf16x8*)(kb + (i & 1) * 32 * A_KROWB + (2 + (i >> 1)) * 32);
;         __builtin_amdgcn_sched_barrier(0);
; #pragma unroll
;         for (int i = 0; i < 4; ++i) st[i & 1] = MFMA32(ka[i], qf[i >> 1], st[i & 1]);
;         __builtin_amdgcn_sched_barrier(0);
; #pragma unroll
;         for (int i = 0; i < 4; ++i) st[i & 1] = MFMA32(kc[i], qf[2 + (i >> 1)], st[i & 1]);
;     ...
; #pragma unroll
;     for (int k2 = 0; k2 < 2; ++k2)
; #pragma unroll
;         for (int i = 0; i < 16; ++i) st[k2][i] = __builtin_amdgcn_exp2f(st[k2][i]);
;     {
;         const f32x16 sv = st[0] + st[1];
;         const float ps = (((sv[0] + sv[1]) + (sv[2] + sv[3])) + ((sv[4] + sv[5]) + (sv[6] + sv[7]))) + (((sv[8] + sv[9]) + (sv[10] + sv[11])) + ((sv[12] + sv[13]) + (sv[14] + sv[15])));
;         l += ps;
;     }
; #pragma unroll
;     for (int k4 = 0; k4 < 4; ++k4) {
;         const int k2 = k4 >> 1, o8 = 8 * (k4 & 1);
;         u32x4 pk;
;         pk.x = pk2(st[k2][o8 + 0], st[k2][o8 + 1]); pk.y = pk2(st[k2][o8 + 2], st[k2][o8 + 3]);
;         pk.z = pk2(st[k2][o8 + 4], st[k2][o8 + 5]); pk.w = pk2(st[k2][o8 + 6], st[k2][o8 + 7]);
;         pb[k4] = __builtin_bit_cast(bf16x8, pk);
;     }
.Lpipe_norescale_l:
	v_exp_f32_e32 v82, v82
	v_exp_f32_e32 v83, v83
	v_exp_f32_e32 v84, v84
	v_exp_f32_e32 v85, v85
	v_exp_f32_e32 v86, v86
	v_exp_f32_e32 v87, v87
	v_exp_f32_e32 v88, v88
	v_exp_f32_e32 v89, v89
	v_exp_f32_e32 v90, v90
	v_exp_f32_e32 v91, v91
	v_exp_f32_e32 v92, v92
	v_exp_f32_e32 v93, v93
	v_exp_f32_e32 v94, v94
	v_exp_f32_e32 v95, v95
	v_exp_f32_e32 v96, v96
	v_exp_f32_e32 v97, v97
	v_exp_f32_e32 v66, v66
	v_exp_f32_e32 v67, v67
	v_exp_f32_e32 v68, v68
	v_exp_f32_e32 v69, v69
	v_exp_f32_e32 v70, v70
	v_exp_f32_e32 v71, v71
	v_exp_f32_e32 v72, v72
	v_exp_f32_e32 v73, v73
	v_exp_f32_e32 v74, v74
	v_exp_f32_e32 v75, v75
	v_exp_f32_e32 v76, v76
	v_exp_f32_e32 v77, v77
	v_exp_f32_e32 v78, v78
	v_exp_f32_e32 v79, v79
	v_exp_f32_e32 v80, v80
	v_exp_f32_e32 v81, v81
	v_cvt_pk_bf16_f32 v216, v82, v83
	v_cvt_pk_bf16_f32 v217, v84, v85
	v_cvt_pk_bf16_f32 v218, v86, v87
	v_cvt_pk_bf16_f32 v219, v88, v89
	v_cvt_pk_bf16_f32 v220, v90, v91
	v_cvt_pk_bf16_f32 v221, v92, v93
	v_cvt_pk_bf16_f32 v222, v94, v95
	v_cvt_pk_bf16_f32 v223, v96, v97
	v_cvt_pk_bf16_f32 v224, v66, v67
	v_cvt_pk_bf16_f32 v225, v68, v69
	v_cvt_pk_bf16_f32 v226, v70, v71
	v_cvt_pk_bf16_f32 v227, v72, v73
	v_cvt_pk_bf16_f32 v228, v74, v75
	v_cvt_pk_bf16_f32 v229, v76, v77
	v_cvt_pk_bf16_f32 v230, v78, v79
	v_cvt_pk_bf16_f32 v231, v80, v81
	v_pk_add_f32 v[68:69], v[84:85], v[68:69]
	v_pk_add_f32 v[66:67], v[82:83], v[66:67]
	v_pk_add_f32 v[72:73], v[88:89], v[72:73]
	v_pk_add_f32 v[70:71], v[86:87], v[70:71]
	v_add_f32_e32 v66, v66, v67
	v_add_f32_e32 v67, v68, v69
	v_add_f32_e32 v66, v66, v67
	v_add_f32_e32 v67, v70, v71
	v_add_f32_e32 v68, v72, v73
	v_pk_add_f32 v[76:77], v[92:93], v[76:77]
	v_pk_add_f32 v[74:75], v[90:91], v[74:75]
	v_add_f32_e32 v67, v67, v68
	v_pk_add_f32 v[80:81], v[96:97], v[80:81]
	v_pk_add_f32 v[78:79], v[94:95], v[78:79]
	v_add_f32_e32 v66, v66, v67
	v_add_f32_e32 v67, v74, v75
	v_add_f32_e32 v68, v76, v77
	v_add_f32_e32 v67, v67, v68
	v_add_f32_e32 v68, v78, v79
	v_add_f32_e32 v69, v80, v81
	v_add_f32_e32 v68, v68, v69
	v_add_f32_e32 v67, v67, v68
	v_add_f32_e32 v66, v66, v67
	v_add_f32_e32 v1, v1, v66
	v_add_u32_e32 v158, 64, v158
	s_mov_b32 s13, s7
	s_add_i32 s4, s7, 1
	s_cmp_lg_u32 s7, 2
	s_cselect_b32 s7, s4, 0
	s_add_i32 s12, s12, 1
	s_cmp_eq_u32 s11, s12
	s_cbranch_scc1 .Lpipe_final
	s_barrier
	s_setprio 1
	s_mul_i32 s98, s13, 0x8c00
	v_add3_u32 v185, s98, v155, v154
	ds_read_b128 v[160:163], v185
	ds_read_b128 v[164:167], v185 offset:32
	ds_read_b128 v[168:171], v185 offset:8704
	ds_read_b128 v[196:199], v185 offset:8736
	s_waitcnt lgkmcnt(11)
	v_mfma_f32_32x32x16_bf16 v[50:65], v[172:175], v[216:219], v[50:65]
	s_waitcnt lgkmcnt(10)
	v_mfma_f32_32x32x16_bf16 v[34:49], v[176:179], v[216:219], v[34:49]
	s_waitcnt lgkmcnt(9)
	v_mfma_f32_32x32x16_bf16 v[18:33], v[180:183], v[216:219], v[18:33]
	s_waitcnt lgkmcnt(8)
	v_mfma_f32_32x32x16_bf16 v[2:17], v[192:195], v[216:219], v[2:17]
	ds_read_b128 v[172:175], v185 offset:64
	ds_read_b128 v[176:179], v185 offset:96
	ds_read_b128 v[180:183], v185 offset:8768
	ds_read_b128 v[192:195], v185 offset:8800
	s_waitcnt lgkmcnt(11)
	v_mfma_f32_32x32x16_bf16 v[50:65], v[200:203], v[220:223], v[50:65]
	s_waitcnt lgkmcnt(10)
	v_mfma_f32_32x32x16_bf16 v[34:49], v[204:207], v[220:223], v[34:49]
	s_waitcnt lgkmcnt(9)
	v_mfma_f32_32x32x16_bf16 v[18:33], v[208:211], v[220:223], v[18:33]
	s_waitcnt lgkmcnt(8)
	v_mfma_f32_32x32x16_bf16 v[2:17], v[212:215], v[220:223], v[2:17]
	ds_read_b128 v[200:203], v191 offset:17472
	ds_read_b128 v[204:207], v191 offset:22080
	ds_read_b128 v[208:211], v191 offset:26688
	ds_read_b128 v[212:215], v191 offset:31296
	s_waitcnt lgkmcnt(11)
	v_mfma_f32_32x32x16_bf16 v[82:97], v[160:163], v[100:103], v[240:255]
	s_waitcnt lgkmcnt(9)
	v_mfma_f32_32x32x16_bf16 v[66:81], v[168:171], v[100:103], v[240:255]
	v_mfma_f32_32x32x16_bf16 v[82:97], v[164:167], v[104:107], v[82:97]
	s_waitcnt lgkmcnt(8)
	v_mfma_f32_32x32x16_bf16 v[66:81], v[196:199], v[104:107], v[66:81]
	ds_read_b128 v[160:163], v191 offset:17504
	ds_read_b128 v[164:167], v191 offset:22112
	ds_read_b128 v[168:171], v191 offset:26720
	ds_read_b128 v[196:199], v191 offset:31328
	s_waitcnt lgkmcnt(11)
	v_mfma_f32_32x32x16_bf16 v[82:97], v[172:175], v[108:111], v[82:97]
	s_waitcnt lgkmcnt(9)
	v_mfma_f32_32x32x16_bf16 v[66:81], v[180:183], v[108:111], v[66:81]
	v_mfma_f32_32x32x16_bf16 v[82:97], v[176:179], v[112:115], v[82:97]
	s_waitcnt lgkmcnt(8)
	v_mfma_f32_32x32x16_bf16 v[66:81], v[192:195], v[112:115], v[66:81]
	s_add_i32 s14, s12, 0x42
	s_cmp_ge_i32 s14, s6
	s_cbranch_scc1 .Lpipe_nost_l
	s_mul_i32 s4, s7, 0x8c00
	s_add_i32 s4, s4, 0
	v_add_u32_e32 v184, s4, v140
	v_add_u32_e32 v185, v184, v139
	v_add_u32_e32 v184, v184, v141
	s_waitcnt vmcnt(3)
	ds_write_b128 v185, v[116:119]
	s_waitcnt vmcnt(2)
	ds_write_b128 v184, v[120:123]
	v_add3_u32 v184, s4, v150, v151
	v_add_u32_e32 v185, v184, v152
	v_add_u32_e32 v184, v184, v153
	v_add_u32_e32 v185, 0x4000, v185
	v_add_u32_e32 v184, 0x4000, v184
	s_waitcnt vmcnt(1)
	ds_write2_b64 v185, v[124:125], v[126:127] offset0:128 offset1:130
	s_waitcnt vmcnt(0)
	ds_write2_b64 v184, v[128:129], v[130:131] offset0:128 offset1:130

; #define MFMA32(a, b, c) __builtin_amdgcn_mfma_f32_32x32x16_bf16((a), (b), (c), 0, 0, 0)
; DI void attn_pv(const unsigned char* sV, int l31, int h, const bf16x8 (&pb)[4], f32x16 (&O)[4]) {
;     ...
;         for (int d = 0; d < 4; ++d) O[d] = MFMA32(va[d], pb[0], O[d]);
;         __builtin_amdgcn_sched_barrier(0);
; #pragma unroll
;         for (int d = 0; d < 4; ++d) va[d] = *(const bf16x8*)(vb + d * 32 * A_VROWB + 64);
;         __builtin_amdgcn_sched_barrier(0);
; #pragma unroll
;         for (int d = 0; d < 4; ++d) O[d] = MFMA32(vc[d], pb[1], O[d]);
;         __builtin_amdgcn_sched_barrier(0);
; #pragma unroll
;         for (int d = 0; d < 4; ++d) vc[d] = *(const bf16x8*)(vb + d * 32 * A_VROWB + 96);
;         __builtin_amdgcn_sched_barrier(0);
; #pragma unroll
;         for (int d = 0; d < 4; ++d) O[d] = MFMA32(va[d], pb[2], O[d]);
;         __builtin_amdgcn_sched_barrier(0);
; #pragma unroll
;         for (int d = 0; d < 4; ++d) O[d] = MFMA32(vc[d], pb[3], O[d]);
; DI void attn_item(const Params& p, unsigned char* lds, int b, int hd, int qb, float lam) {
;     ...
;         if (tt + 1 < T) A_STORE(k0r, v0r, bn);
;         __syncthreads();
;         bp = bc; bc = bn; bn = (bn == 2) ? 0 : bn + 1;
;     }
.Lpipe_nopf_l:
	s_waitcnt lgkmcnt(7)
	v_mfma_f32_32x32x16_bf16 v[50:65], v[200:203], v[224:227], v[50:65]
	s_waitcnt lgkmcnt(6)
	v_mfma_f32_32x32x16_bf16 v[34:49], v[204:207], v[224:227], v[34:49]
	s_waitcnt lgkmcnt(5)
	v_mfma_f32_32x32x16_bf16 v[18:33], v[208:211], v[224:227], v[18:33]
	s_waitcnt lgkmcnt(4)
	v_mfma_f32_32x32x16_bf16 v[2:17], v[212:215], v[224:227], v[2:17]
	s_waitcnt lgkmcnt(3)
	v_mfma_f32_32x32x16_bf16 v[50:65], v[160:163], v[228:231], v[50:65]
	s_waitcnt lgkmcnt(2)
	v_mfma_f32_32x32x16_bf16 v[34:49], v[164:167], v[228:231], v[34:49]
	s_waitcnt lgkmcnt(1)
	v_mfma_f32_32x32x16_bf16 v[18:33], v[168:171], v[228:231], v[18:33]
	s_waitcnt lgkmcnt(0)
	v_mfma_f32_32x32x16_bf16 v[2:17], v[196:199], v[228:231], v[2:17]
	s_setprio 0
	s_waitcnt lgkmcnt(0)
	s_barrier
	s_branch .Lpipe_loop
